# attention work-queue: next item's ticket requested when the current item starts (hidden atomic latency), not for the last 64 tickets of a queue
# speedup vs baseline: 1.0057x; 1.0057x over previous
; __device__ __forceinline__ int otid() { int t = threadIdx.x; asm volatile("" : "+v"(t)); return t; }
; #define LASP __attribute__((address_space(3)))
; __device__ __forceinline__ void p4_attn(const Params& P, int l, bool last, unsigned char* smem) {
;     ...
;     for (int pr = 0; pr < 8; ++pr) {
;         const int q = (int)((x0 + pr) & 7u);
;         for (;;) {
;             volatile LASP unsigned* slot = (volatile LASP unsigned*)((LASP unsigned char*)smem + 131072 + 8);
;             __syncthreads();
;             if (otid() == 0) *slot = __hip_atomic_fetch_add((unsigned*)(PWS + WS_Q) + (size_t)(l * 8 + q) * 64, 1u, __ATOMIC_RELAXED, __HIP_MEMORY_SCOPE_AGENT);
.LBB0_818:
	s_mov_b32 s98, 0
	s_add_i32 s2, s9, s6
	s_and_b32 s12, s2, 7
	s_lshl_b32 s2, s12, 8
	s_mul_i32 s10, s12, 12
	s_or_b32 s2, s2, s8
	s_add_i32 s11, s10, 0xffffff34
	v_readlane_b32 s3, v255, 17
	s_add_u32 s24, s3, s2
	v_readlane_b32 s2, v255, 18
	s_mul_i32 s12, s12, 6
	s_addc_u32 s25, s2, 0
	s_branch .LBB0_823

; __device__ __forceinline__ int otid() { int t = threadIdx.x; asm volatile("" : "+v"(t)); return t; }
; #define LASP __attribute__((address_space(3)))
; __device__ __forceinline__ void p4_attn(const Params& P, int l, bool last, unsigned char* smem) {
;     ...
;         for (;;) {
;             volatile LASP unsigned* slot = (volatile LASP unsigned*)((LASP unsigned char*)smem + 131072 + 8);
;             __syncthreads();
;             if (otid() == 0) *slot = __hip_atomic_fetch_add((unsigned*)(PWS + WS_Q) + (size_t)(l * 8 + q) * 64, 1u, __ATOMIC_RELAXED, __HIP_MEMORY_SCOPE_AGENT);
;             __syncthreads();
;             const int i = __builtin_amdgcn_readfirstlane((int)*slot);
;             if (i >= nq) break;
.LBB0_823:
	v_cmp_eq_u32_e32 vcc, 0, v253
	s_and_saveexec_b64 s[2:3], vcc
	s_cbranch_execz .Ldisp_pre
	s_cmp_lg_u32 s98, 0
	s_cbranch_scc1 .Ldisp_pre
	v_mov_b32_e32 v217, 1
	s_nop 0
	global_atomic_add v217, v0, v217, s[24:25] sc0
.Ldisp_pre:
	s_or_b64 exec, exec, s[2:3]
	s_barrier
	v_cmp_eq_u32_e32 vcc, 0, v253
	s_and_saveexec_b64 s[2:3], vcc
	s_cbranch_execz .LBB0_827
	s_waitcnt vmcnt(0)
	v_mov_b32_e32 v2, s94
	s_nop 0
	ds_write_b32 v2, v217
.LBB0_827:
	s_or_b64 exec, exec, s[2:3]
	v_mov_b32_e32 v1, s94
	s_waitcnt lgkmcnt(0)
	s_barrier
	ds_read_b32 v1, v1
	s_mov_b64 s[2:3], -1
	s_mov_b32 s98, 0
	s_waitcnt lgkmcnt(0)
	v_readfirstlane_b32 s13, v1
	s_cmp_ge_i32 s13, s7
	s_cbranch_scc1 .LBB0_822
	s_sub_i32 s5, s7, 64
	s_cmp_ge_i32 s13, s5
	s_cbranch_scc1 .Ldisp_nopf
	s_mov_b32 s98, 1
	v_cmp_eq_u32_e32 vcc, 0, v253
	s_and_saveexec_b64 s[100:101], vcc
	s_cbranch_execz .Ldisp_pf_done
	v_mov_b32_e32 v217, 1
	s_nop 0
	global_atomic_add v217, v0, v217, s[24:25] sc0

; #define PIN(i) ((const float*)(const GASP float*)karg_q(i))
; __device__ __forceinline__ void p4_attn(const Params& P, int l, bool last, unsigned char* smem) {
;     ...
;             if (i >= nq) break;
;             unsigned char* ws = PWS;
;             const bf16_t* U = (const bf16_t*)(ws + WS_U);
;             bf16_t* O = (bf16_t*)(ws + WS_AO);
;             if (i >= 96 && i < 192) {
;                 const int j = i - 96, bp = q * 6 + (j >> 4), r = j & 15;
;                 na_item(smem, U, PIN(11) + (size_t)l * 6 * 15 * 31, O, bp / 3, r, bp % 3, shift_nal);
;             } else if (i >= 204) {
.Ldisp_nopf:
	s_add_i32 s26, s13, 0xffffffa0
	s_cmpk_gt_u32 s26, 0x5f
	s_cbranch_scc0 .LBB0_838
	s_cmpk_lt_i32 s13, 0xcc
	s_cbranch_scc0 .LBB0_835
	v_readfirstlane_b32 s99, v253
	s_cmp_lt_u32 s99, 0x100
	s_cbranch_scc1 .Lprio_mla_skip
	s_setprio 1

; __device__ __forceinline__ void xcd_barrier(const XcdBarrier& b) {
;     asm volatile("s_waitcnt vmcnt(0)" ::: "memory");
;     __syncthreads();
;     if (threadIdx.x == 0) {
;         unsigned* bar = b.bar;
;         __builtin_amdgcn_s_waitcnt(0);
;         unsigned nloc = b.st[0], nx = b.st[1];
;         if (nloc == 0u) { xcd_barrier_complete(bar, b.x, nloc, nx); b.st[0] = nloc; b.st[1] = nx; }
.LBB0_894:
	v_mov_b32_e32 v217, 0x1200
	s_waitcnt vmcnt(0)
	v_readlane_b32 s12, v255, 32
	v_readlane_b32 s13, v255, 33
	s_barrier
	s_and_saveexec_b64 s[2:3], s[12:13]
	v_readlane_b32 s52, v255, 35
	v_readlane_b32 s60, v255, 37
	v_readlane_b32 s18, v255, 49
	v_readlane_b32 s63, v254, 0
	v_readlane_b32 s62, v255, 34
	v_readlane_b32 s53, v255, 36
	v_readlane_b32 s61, v255, 38
	v_readlane_b32 s19, v255, 50
	s_cbranch_execz .LBB0_946
	v_readlane_b32 s5, v255, 27
	s_waitcnt vmcnt(0) expcnt(0) lgkmcnt(0)
	s_nop 0
	v_mov_b32_e32 v1, s5
	ds_read_b32 v3, v1
	v_readlane_b32 s5, v255, 28
	s_waitcnt lgkmcnt(0)
	v_cmp_ne_u32_e32 vcc, 0, v3
	v_mov_b32_e32 v1, s5
	ds_read_b32 v2, v1
	s_cbranch_vccnz .LBB0_910
	s_mov_b32 s5, 1
	s_branch .LBB0_898
